# EpiSwiGLU float section rewritten: packed mul/add, 8 exps then 8 rcps per block (same math and rounding order)
# speedup vs baseline: 1.0160x; 1.0007x over previous
; __device__ __forceinline__ u32x4 pack8(f32x4 a, f32x4 b) { u32x4 w; w.x = pk2(a[0], a[1]); w.y = pk2(a[2], a[3]); w.z = pk2(b[0], b[1]); w.w = pk2(b[2], b[3]); return w; }
; __device__ __forceinline__ float fast_sigmoid(float x) { return __builtin_amdgcn_rcpf(1.0f + __builtin_amdgcn_exp2f(-x * LOG2E)); }
; __device__ __forceinline__ float row_rs16(const float* ssq_x, int row) {
;     const f32x4* p = (const f32x4*)(ssq_x + (size_t)row * 16); const f32x4 a = p[0], b = p[1], c = p[2], d = p[3];
;     return rsqrtf((((a[0] + a[1]) + (a[2] + a[3])) + ((b[0] + b[1]) + (b[2] + b[3])) + ((c[0] + c[1]) + (c[2] + c[3])) + ((d[0] + d[1]) + (d[2] + d[3]))) * (1.0f / DM) + EPS);
; }
;     __device__ __forceinline__ void operator()(const Acc& acc, const Unit& u, int wr, int wc, int fr, int fq, const RsCtx& rc) const {
;     ...
;             for (int m = 0; m < 4; ++m) { const int row = EPI_ROW(u, ai, wr, m, fr); const float rs = rc.get(u.pm, ai * 128 + wr * 64 + m * 16 + fr, row);
;                 f32x4 a0 = acc[ai][0][m][0] * rs, a1 = acc[ai][0][m][1] * rs; const f32x4 b0 = acc[ai][1][m][0] * rs, b1 = acc[ai][1][m][1] * rs;
; #pragma unroll
;                 for (int e = 0; e < 4; ++e) { a0[e] = a0[e] * fast_sigmoid(a0[e]) * b0[e]; a1[e] = a1[e] * fast_sigmoid(a1[e]) * b1[e]; }
;                 *(u32x4*)(O + (size_t)row * FF + col) = pack8(a0, a1);
;                 if (m == 3) asm volatile("" ::: "memory"); }
.LBB0_155:
	s_waitcnt lgkmcnt(0)
	v_lshl_or_b32 v140, s36, 7, v148
	v_readlane_b32 s6, v255, 0
	v_ashrrev_i32_e32 v141, 31, v140
	v_readlane_b32 s7, v255, 1
	v_lshl_add_u64 v[140:141], v[140:141], 1, s[6:7]
	s_mov_b64 s[28:29], -1
	s_andn2_b64 vcc, exec, s[24:25]
	s_mov_b32 s100, 0xbfb8aa3b
	v_pk_mul_f32 v[126:127], v[126:127], v[144:145] op_sel_hi:[1,0]
	v_pk_mul_f32 v[128:129], v[128:129], v[144:145] op_sel_hi:[1,0]
	v_pk_mul_f32 v[122:123], v[122:123], v[144:145] op_sel_hi:[1,0]
	v_pk_mul_f32 v[124:125], v[124:125], v[144:145] op_sel_hi:[1,0]
	v_pk_mul_f32 v[150:151], v[126:127], s[100:101] op_sel_hi:[1,0]
	v_pk_mul_f32 v[152:153], v[128:129], s[100:101] op_sel_hi:[1,0]
	v_pk_mul_f32 v[154:155], v[122:123], s[100:101] op_sel_hi:[1,0]
	v_pk_mul_f32 v[156:157], v[124:125], s[100:101] op_sel_hi:[1,0]
	s_mov_b32 s100, 1.0
	v_exp_f32_e32 v150, v150
	v_exp_f32_e32 v151, v151
	v_exp_f32_e32 v152, v152
	v_exp_f32_e32 v153, v153
	v_exp_f32_e32 v154, v154
	v_exp_f32_e32 v155, v155
	v_exp_f32_e32 v156, v156
	v_exp_f32_e32 v157, v157
	v_pk_mul_f32 v[118:119], v[118:119], v[144:145] op_sel_hi:[1,0]
	v_pk_mul_f32 v[120:121], v[120:121], v[144:145] op_sel_hi:[1,0]
	v_pk_mul_f32 v[114:115], v[114:115], v[144:145] op_sel_hi:[1,0]
	v_pk_mul_f32 v[116:117], v[116:117], v[144:145] op_sel_hi:[1,0]
	v_pk_add_f32 v[150:151], v[150:151], s[100:101] op_sel_hi:[1,0]
	v_pk_add_f32 v[152:153], v[152:153], s[100:101] op_sel_hi:[1,0]
	v_pk_add_f32 v[154:155], v[154:155], s[100:101] op_sel_hi:[1,0]
	v_pk_add_f32 v[156:157], v[156:157], s[100:101] op_sel_hi:[1,0]
	v_rcp_f32_e32 v150, v150
	v_rcp_f32_e32 v151, v151
	v_rcp_f32_e32 v152, v152
	v_rcp_f32_e32 v153, v153
	v_rcp_f32_e32 v154, v154
	v_rcp_f32_e32 v155, v155
	v_rcp_f32_e32 v156, v156
	v_rcp_f32_e32 v157, v157
	v_pk_mul_f32 v[126:127], v[126:127], v[150:151]
	v_pk_mul_f32 v[128:129], v[128:129], v[152:153]
	v_pk_mul_f32 v[122:123], v[122:123], v[154:155]
	v_pk_mul_f32 v[124:125], v[124:125], v[156:157]
	v_pk_mul_f32 v[118:119], v[118:119], v[126:127]
	v_pk_mul_f32 v[120:121], v[120:121], v[128:129]
	v_pk_mul_f32 v[122:123], v[114:115], v[122:123]
	v_pk_mul_f32 v[124:125], v[116:117], v[124:125]
	v_cvt_pk_bf16_f32 v114, v118, v119
	v_cvt_pk_bf16_f32 v115, v120, v121
	v_cvt_pk_bf16_f32 v116, v122, v123
	v_cvt_pk_bf16_f32 v117, v124, v125
	v_mad_i64_i32 v[118:119], s[6:7], v142, s64, v[140:141]
	flat_store_dwordx4 v[118:119], v[114:117]
	s_nop 1
	v_cndmask_b32_e64 v115, 0, 1, s[24:25]
	v_or_b32_e32 v114, 16, v142
	v_cmp_ne_u32_e64 s[6:7], 1, v115
	s_cbranch_vccnz .LBB0_161
	s_cmp_eq_u32 s48, s12
	s_mov_b64 s[24:25], -1
	s_cbranch_scc1 .LBB0_158
	v_ashrrev_i32_e32 v115, 31, v114
	v_lshlrev_b64 v[116:117], 6, v[114:115]
	v_lshl_add_u64 v[128:129], s[38:39], 0, v[116:117]
	flat_load_dwordx4 v[116:119], v[128:129]
	flat_load_dwordx4 v[120:123], v[128:129] offset:16
	flat_load_dwordx4 v[124:127], v[128:129] offset:32
	flat_load_dwordx4 v[150:153], v[128:129] offset:48
	s_mov_b64 s[24:25], 0
	s_waitcnt vmcnt(0) lgkmcnt(0)
	v_mov_b32_e32 v128, v117
	v_mov_b32_e32 v129, v118
	v_mov_b32_e32 v117, v119
	v_mov_b32_e32 v118, v121
	v_mov_b32_e32 v119, v122
	v_mov_b32_e32 v121, v123
	v_pk_add_f32 v[116:117], v[128:129], v[116:117]
	v_pk_add_f32 v[118:119], v[118:119], v[120:121]
	v_pk_add_f32 v[116:117], v[116:117], v[116:117] op_sel:[0,1] op_sel_hi:[1,0]
	v_pk_add_f32 v[118:119], v[118:119], v[118:119] op_sel:[0,1] op_sel_hi:[1,0]
	v_add_f32_e32 v120, v124, v125
	v_add_f32_e32 v122, v126, v127
	v_mov_b32_e32 v117, v150
	v_mov_b32_e32 v119, v151
	v_mov_b32_e32 v121, v152
	v_mov_b32_e32 v123, v153
	v_pk_add_f32 v[116:117], v[116:117], v[118:119]
	v_pk_add_f32 v[118:119], v[120:121], v[122:123]
	s_nop 0
	v_pk_add_f32 v[116:117], v[116:117], v[118:119]
	s_nop 0
	v_add_f32_e32 v115, v116, v117
	v_fmamk_f32 v115, v115, 0x3a800000, v205
	v_cmp_gt_f32_e32 vcc, s77, v115
	v_mul_f32_e32 v116, 0x4b800000, v115
	s_nop 0
	v_cndmask_b32_e32 v115, v115, v116, vcc
	v_rsq_f32_e32 v115, v115
	s_nop 0
	v_mul_f32_e32 v116, 0x45800000, v115
	v_cndmask_b32_e32 v116, v115, v116, vcc

; __device__ __forceinline__ u32x4 pack8(f32x4 a, f32x4 b) { u32x4 w; w.x = pk2(a[0], a[1]); w.y = pk2(a[2], a[3]); w.z = pk2(b[0], b[1]); w.w = pk2(b[2], b[3]); return w; }
; __device__ __forceinline__ float fast_sigmoid(float x) { return __builtin_amdgcn_rcpf(1.0f + __builtin_amdgcn_exp2f(-x * LOG2E)); }
; __device__ __forceinline__ float row_rs16(const float* ssq_x, int row) {
;     const f32x4* p = (const f32x4*)(ssq_x + (size_t)row * 16); const f32x4 a = p[0], b = p[1], c = p[2], d = p[3];
;     return rsqrtf((((a[0] + a[1]) + (a[2] + a[3])) + ((b[0] + b[1]) + (b[2] + b[3])) + ((c[0] + c[1]) + (c[2] + c[3])) + ((d[0] + d[1]) + (d[2] + d[3]))) * (1.0f / DM) + EPS);
; }
;     __device__ __forceinline__ void operator()(const Acc& acc, const Unit& u, int wr, int wc, int fr, int fq, const RsCtx& rc) const {
;     ...
;             for (int m = 0; m < 4; ++m) { const int row = EPI_ROW(u, ai, wr, m, fr); const float rs = rc.get(u.pm, ai * 128 + wr * 64 + m * 16 + fr, row);
;                 f32x4 a0 = acc[ai][0][m][0] * rs, a1 = acc[ai][0][m][1] * rs; const f32x4 b0 = acc[ai][1][m][0] * rs, b1 = acc[ai][1][m][1] * rs;
; #pragma unroll
;                 for (int e = 0; e < 4; ++e) { a0[e] = a0[e] * fast_sigmoid(a0[e]) * b0[e]; a1[e] = a1[e] * fast_sigmoid(a1[e]) * b1[e]; }
;                 *(u32x4*)(O + (size_t)row * FF + col) = pack8(a0, a1);
;                 if (m == 3) asm volatile("" ::: "memory"); }
.LBB0_163:
	s_waitcnt lgkmcnt(0)
	s_and_b64 vcc, exec, s[6:7]
	s_mov_b32 s100, 0xbfb8aa3b
	v_pk_mul_f32 v[110:111], v[110:111], v[116:117] op_sel_hi:[1,0]
	v_pk_mul_f32 v[112:113], v[112:113], v[116:117] op_sel_hi:[1,0]
	v_pk_mul_f32 v[106:107], v[106:107], v[116:117] op_sel_hi:[1,0]
	v_pk_mul_f32 v[108:109], v[108:109], v[116:117] op_sel_hi:[1,0]
	v_pk_mul_f32 v[118:119], v[110:111], s[100:101] op_sel_hi:[1,0]
	v_pk_mul_f32 v[120:121], v[112:113], s[100:101] op_sel_hi:[1,0]
	v_pk_mul_f32 v[122:123], v[106:107], s[100:101] op_sel_hi:[1,0]
	v_pk_mul_f32 v[124:125], v[108:109], s[100:101] op_sel_hi:[1,0]
	s_mov_b32 s100, 1.0
	v_exp_f32_e32 v118, v118
	v_exp_f32_e32 v119, v119
	v_exp_f32_e32 v120, v120
	v_exp_f32_e32 v121, v121
	v_exp_f32_e32 v122, v122
	v_exp_f32_e32 v123, v123
	v_exp_f32_e32 v124, v124
	v_exp_f32_e32 v125, v125
	v_pk_mul_f32 v[102:103], v[102:103], v[116:117] op_sel_hi:[1,0]
	v_pk_mul_f32 v[104:105], v[104:105], v[116:117] op_sel_hi:[1,0]
	v_pk_mul_f32 v[98:99], v[98:99], v[116:117] op_sel_hi:[1,0]
	v_pk_mul_f32 v[100:101], v[100:101], v[116:117] op_sel_hi:[1,0]
	v_pk_add_f32 v[118:119], v[118:119], s[100:101] op_sel_hi:[1,0]
	v_pk_add_f32 v[120:121], v[120:121], s[100:101] op_sel_hi:[1,0]
	v_pk_add_f32 v[122:123], v[122:123], s[100:101] op_sel_hi:[1,0]
	v_pk_add_f32 v[124:125], v[124:125], s[100:101] op_sel_hi:[1,0]
	v_rcp_f32_e32 v118, v118
	v_rcp_f32_e32 v119, v119
	v_rcp_f32_e32 v120, v120
	v_rcp_f32_e32 v121, v121
	v_rcp_f32_e32 v122, v122
	v_rcp_f32_e32 v123, v123
	v_rcp_f32_e32 v124, v124
	v_rcp_f32_e32 v125, v125
	v_pk_mul_f32 v[110:111], v[110:111], v[118:119]
	v_pk_mul_f32 v[112:113], v[112:113], v[120:121]
	v_pk_mul_f32 v[106:107], v[106:107], v[122:123]
	v_pk_mul_f32 v[108:109], v[108:109], v[124:125]
	v_pk_mul_f32 v[102:103], v[102:103], v[110:111]
	v_pk_mul_f32 v[104:105], v[104:105], v[112:113]
	v_pk_mul_f32 v[106:107], v[98:99], v[106:107]
	v_pk_mul_f32 v[108:109], v[100:101], v[108:109]
	v_cvt_pk_bf16_f32 v98, v102, v103
	v_cvt_pk_bf16_f32 v99, v104, v105
	v_cvt_pk_bf16_f32 v100, v106, v107
	v_cvt_pk_bf16_f32 v101, v108, v109
	v_mad_i64_i32 v[102:103], s[24:25], v114, s64, v[140:141]
	flat_store_dwordx4 v[102:103], v[98:101]
	s_mov_b64 s[24:25], -1
	s_nop 0
	v_or_b32_e32 v98, 32, v142
	s_cbranch_vccnz .LBB0_169
	s_cmp_eq_u32 s48, s12
	s_cbranch_scc1 .LBB0_166
	v_ashrrev_i32_e32 v99, 31, v98
	v_lshlrev_b64 v[100:101], 6, v[98:99]
	v_lshl_add_u64 v[112:113], s[38:39], 0, v[100:101]
	flat_load_dwordx4 v[100:103], v[112:113]
	flat_load_dwordx4 v[104:107], v[112:113] offset:16
	flat_load_dwordx4 v[108:111], v[112:113] offset:32
	s_nop 0
	flat_load_dwordx4 v[112:115], v[112:113] offset:48
	s_mov_b64 s[24:25], 0
	s_waitcnt vmcnt(0) lgkmcnt(0)
	v_mov_b32_e32 v116, v101
	v_mov_b32_e32 v117, v102
	v_mov_b32_e32 v101, v103
	v_mov_b32_e32 v102, v105
	v_mov_b32_e32 v103, v106
	v_mov_b32_e32 v105, v107
	v_pk_add_f32 v[100:101], v[116:117], v[100:101]
	v_pk_add_f32 v[102:103], v[102:103], v[104:105]
	v_pk_add_f32 v[100:101], v[100:101], v[100:101] op_sel:[0,1] op_sel_hi:[1,0]
	v_pk_add_f32 v[102:103], v[102:103], v[102:103] op_sel:[0,1] op_sel_hi:[1,0]
	v_add_f32_e32 v104, v108, v109
	v_add_f32_e32 v106, v110, v111
	v_mov_b32_e32 v101, v112
	v_mov_b32_e32 v103, v113
	v_mov_b32_e32 v105, v114
	v_mov_b32_e32 v107, v115
	v_pk_add_f32 v[100:101], v[100:101], v[102:103]
	v_pk_add_f32 v[102:103], v[104:105], v[106:107]
	s_nop 0
	v_pk_add_f32 v[100:101], v[100:101], v[102:103]
	s_nop 0
	v_add_f32_e32 v99, v100, v101
	v_fmamk_f32 v99, v99, 0x3a800000, v205
	v_cmp_gt_f32_e32 vcc, s77, v99
	v_mul_f32_e32 v100, 0x4b800000, v99
	s_nop 0
	v_cndmask_b32_e32 v99, v99, v100, vcc
	v_rsq_f32_e32 v99, v99
	s_nop 0
	v_mul_f32_e32 v100, 0x45800000, v99
	v_cndmask_b32_e32 v100, v99, v100, vcc

; __device__ __forceinline__ u32x4 pack8(f32x4 a, f32x4 b) { u32x4 w; w.x = pk2(a[0], a[1]); w.y = pk2(a[2], a[3]); w.z = pk2(b[0], b[1]); w.w = pk2(b[2], b[3]); return w; }
; __device__ __forceinline__ float fast_sigmoid(float x) { return __builtin_amdgcn_rcpf(1.0f + __builtin_amdgcn_exp2f(-x * LOG2E)); }
; __device__ __forceinline__ float row_rs16(const float* ssq_x, int row) {
;     const f32x4* p = (const f32x4*)(ssq_x + (size_t)row * 16); const f32x4 a = p[0], b = p[1], c = p[2], d = p[3];
;     return rsqrtf((((a[0] + a[1]) + (a[2] + a[3])) + ((b[0] + b[1]) + (b[2] + b[3])) + ((c[0] + c[1]) + (c[2] + c[3])) + ((d[0] + d[1]) + (d[2] + d[3]))) * (1.0f / DM) + EPS);
; }
;     __device__ __forceinline__ void operator()(const Acc& acc, const Unit& u, int wr, int wc, int fr, int fq, const RsCtx& rc) const {
;     ...
;             for (int m = 0; m < 4; ++m) { const int row = EPI_ROW(u, ai, wr, m, fr); const float rs = rc.get(u.pm, ai * 128 + wr * 64 + m * 16 + fr, row);
;                 f32x4 a0 = acc[ai][0][m][0] * rs, a1 = acc[ai][0][m][1] * rs; const f32x4 b0 = acc[ai][1][m][0] * rs, b1 = acc[ai][1][m][1] * rs;
; #pragma unroll
;                 for (int e = 0; e < 4; ++e) { a0[e] = a0[e] * fast_sigmoid(a0[e]) * b0[e]; a1[e] = a1[e] * fast_sigmoid(a1[e]) * b1[e]; }
;                 *(u32x4*)(O + (size_t)row * FF + col) = pack8(a0, a1);
;                 if (m == 3) asm volatile("" ::: "memory"); }
.LBB0_171:
	s_waitcnt lgkmcnt(0)
	s_and_b64 vcc, exec, s[6:7]
	s_mov_b32 s100, 0xbfb8aa3b
	v_pk_mul_f32 v[94:95], v[94:95], v[100:101] op_sel_hi:[1,0]
	v_pk_mul_f32 v[96:97], v[96:97], v[100:101] op_sel_hi:[1,0]
	v_pk_mul_f32 v[90:91], v[90:91], v[100:101] op_sel_hi:[1,0]
	v_pk_mul_f32 v[92:93], v[92:93], v[100:101] op_sel_hi:[1,0]
	v_pk_mul_f32 v[102:103], v[94:95], s[100:101] op_sel_hi:[1,0]
	v_pk_mul_f32 v[104:105], v[96:97], s[100:101] op_sel_hi:[1,0]
	v_pk_mul_f32 v[106:107], v[90:91], s[100:101] op_sel_hi:[1,0]
	v_pk_mul_f32 v[108:109], v[92:93], s[100:101] op_sel_hi:[1,0]
	s_mov_b32 s100, 1.0
	v_exp_f32_e32 v102, v102
	v_exp_f32_e32 v103, v103
	v_exp_f32_e32 v104, v104
	v_exp_f32_e32 v105, v105
	v_exp_f32_e32 v106, v106
	v_exp_f32_e32 v107, v107
	v_exp_f32_e32 v108, v108
	v_exp_f32_e32 v109, v109
	v_pk_mul_f32 v[86:87], v[86:87], v[100:101] op_sel_hi:[1,0]
	v_pk_mul_f32 v[88:89], v[88:89], v[100:101] op_sel_hi:[1,0]
	v_pk_mul_f32 v[82:83], v[82:83], v[100:101] op_sel_hi:[1,0]
	v_pk_mul_f32 v[84:85], v[84:85], v[100:101] op_sel_hi:[1,0]
	v_pk_add_f32 v[102:103], v[102:103], s[100:101] op_sel_hi:[1,0]
	v_pk_add_f32 v[104:105], v[104:105], s[100:101] op_sel_hi:[1,0]
	v_pk_add_f32 v[106:107], v[106:107], s[100:101] op_sel_hi:[1,0]
	v_pk_add_f32 v[108:109], v[108:109], s[100:101] op_sel_hi:[1,0]
	v_rcp_f32_e32 v102, v102
	v_rcp_f32_e32 v103, v103
	v_rcp_f32_e32 v104, v104
	v_rcp_f32_e32 v105, v105
	v_rcp_f32_e32 v106, v106
	v_rcp_f32_e32 v107, v107
	v_rcp_f32_e32 v108, v108
	v_rcp_f32_e32 v109, v109
	v_pk_mul_f32 v[94:95], v[94:95], v[102:103]
	v_pk_mul_f32 v[96:97], v[96:97], v[104:105]
	v_pk_mul_f32 v[90:91], v[90:91], v[106:107]
	v_pk_mul_f32 v[92:93], v[92:93], v[108:109]
	v_pk_mul_f32 v[86:87], v[86:87], v[94:95]
	v_pk_mul_f32 v[88:89], v[88:89], v[96:97]
	v_pk_mul_f32 v[90:91], v[82:83], v[90:91]
	v_pk_mul_f32 v[92:93], v[84:85], v[92:93]
	v_cvt_pk_bf16_f32 v82, v86, v87
	v_cvt_pk_bf16_f32 v83, v88, v89
	v_cvt_pk_bf16_f32 v84, v90, v91
	v_cvt_pk_bf16_f32 v85, v92, v93
	v_mad_i64_i32 v[86:87], s[24:25], v98, s64, v[140:141]
	flat_store_dwordx4 v[86:87], v[82:85]
	s_mov_b64 s[24:25], -1
	s_nop 0
	v_or_b32_e32 v82, 48, v142
	s_cbranch_vccnz .LBB0_177
	s_cmp_eq_u32 s48, s12
	s_cbranch_scc1 .LBB0_174
	v_ashrrev_i32_e32 v83, 31, v82
	v_lshlrev_b64 v[84:85], 6, v[82:83]
	v_lshl_add_u64 v[96:97], s[38:39], 0, v[84:85]
	flat_load_dwordx4 v[84:87], v[96:97]
	flat_load_dwordx4 v[88:91], v[96:97] offset:16
	flat_load_dwordx4 v[92:95], v[96:97] offset:32
	s_nop 0
	flat_load_dwordx4 v[96:99], v[96:97] offset:48
	s_mov_b64 s[24:25], 0
	s_waitcnt vmcnt(0) lgkmcnt(0)
	v_mov_b32_e32 v100, v85
	v_mov_b32_e32 v101, v86
	v_mov_b32_e32 v85, v87
	v_mov_b32_e32 v86, v89
	v_mov_b32_e32 v87, v90
	v_mov_b32_e32 v89, v91
	v_pk_add_f32 v[84:85], v[100:101], v[84:85]
	v_pk_add_f32 v[86:87], v[86:87], v[88:89]
	v_pk_add_f32 v[84:85], v[84:85], v[84:85] op_sel:[0,1] op_sel_hi:[1,0]
	v_pk_add_f32 v[86:87], v[86:87], v[86:87] op_sel:[0,1] op_sel_hi:[1,0]
	v_add_f32_e32 v88, v92, v93
	v_add_f32_e32 v90, v94, v95
	v_mov_b32_e32 v85, v96
	v_mov_b32_e32 v87, v97
	v_mov_b32_e32 v89, v98
	v_mov_b32_e32 v91, v99
	v_pk_add_f32 v[84:85], v[84:85], v[86:87]
	v_pk_add_f32 v[86:87], v[88:89], v[90:91]
	s_nop 0
	v_pk_add_f32 v[84:85], v[84:85], v[86:87]
	s_nop 0
	v_add_f32_e32 v83, v84, v85
	v_fmamk_f32 v83, v83, 0x3a800000, v205
	v_cmp_gt_f32_e32 vcc, s77, v83
	v_mul_f32_e32 v84, 0x4b800000, v83
	s_nop 0
	v_cndmask_b32_e32 v83, v83, v84, vcc
	v_rsq_f32_e32 v83, v83
	s_nop 0
	v_mul_f32_e32 v84, 0x45800000, v83
	v_cndmask_b32_e32 v84, v83, v84, vcc

; __device__ __forceinline__ u32x4 pack8(f32x4 a, f32x4 b) { u32x4 w; w.x = pk2(a[0], a[1]); w.y = pk2(a[2], a[3]); w.z = pk2(b[0], b[1]); w.w = pk2(b[2], b[3]); return w; }
; __device__ __forceinline__ float fast_sigmoid(float x) { return __builtin_amdgcn_rcpf(1.0f + __builtin_amdgcn_exp2f(-x * LOG2E)); }
; __device__ __forceinline__ float row_rs16(const float* ssq_x, int row) {
;     const f32x4* p = (const f32x4*)(ssq_x + (size_t)row * 16); const f32x4 a = p[0], b = p[1], c = p[2], d = p[3];
;     return rsqrtf((((a[0] + a[1]) + (a[2] + a[3])) + ((b[0] + b[1]) + (b[2] + b[3])) + ((c[0] + c[1]) + (c[2] + c[3])) + ((d[0] + d[1]) + (d[2] + d[3]))) * (1.0f / DM) + EPS);
; }
;     __device__ __forceinline__ void operator()(const Acc& acc, const Unit& u, int wr, int wc, int fr, int fq, const RsCtx& rc) const {
;     ...
;             for (int m = 0; m < 4; ++m) { const int row = EPI_ROW(u, ai, wr, m, fr); const float rs = rc.get(u.pm, ai * 128 + wr * 64 + m * 16 + fr, row);
;                 f32x4 a0 = acc[ai][0][m][0] * rs, a1 = acc[ai][0][m][1] * rs; const f32x4 b0 = acc[ai][1][m][0] * rs, b1 = acc[ai][1][m][1] * rs;
; #pragma unroll
;                 for (int e = 0; e < 4; ++e) { a0[e] = a0[e] * fast_sigmoid(a0[e]) * b0[e]; a1[e] = a1[e] * fast_sigmoid(a1[e]) * b1[e]; }
;                 *(u32x4*)(O + (size_t)row * FF + col) = pack8(a0, a1);
.LBB0_179:
	s_waitcnt lgkmcnt(0)
	s_and_b64 vcc, exec, s[6:7]
	s_mov_b32 s100, 0xbfb8aa3b
	v_pk_mul_f32 v[78:79], v[78:79], v[84:85] op_sel_hi:[1,0]
	v_pk_mul_f32 v[80:81], v[80:81], v[84:85] op_sel_hi:[1,0]
	v_pk_mul_f32 v[74:75], v[74:75], v[84:85] op_sel_hi:[1,0]
	v_pk_mul_f32 v[76:77], v[76:77], v[84:85] op_sel_hi:[1,0]
	v_pk_mul_f32 v[86:87], v[78:79], s[100:101] op_sel_hi:[1,0]
	v_pk_mul_f32 v[88:89], v[80:81], s[100:101] op_sel_hi:[1,0]
	v_pk_mul_f32 v[90:91], v[74:75], s[100:101] op_sel_hi:[1,0]
	v_pk_mul_f32 v[92:93], v[76:77], s[100:101] op_sel_hi:[1,0]
	s_mov_b32 s100, 1.0
	v_exp_f32_e32 v86, v86
	v_exp_f32_e32 v87, v87
	v_exp_f32_e32 v88, v88
	v_exp_f32_e32 v89, v89
	v_exp_f32_e32 v90, v90
	v_exp_f32_e32 v91, v91
	v_exp_f32_e32 v92, v92
	v_exp_f32_e32 v93, v93
	v_pk_mul_f32 v[70:71], v[70:71], v[84:85] op_sel_hi:[1,0]
	v_pk_mul_f32 v[72:73], v[72:73], v[84:85] op_sel_hi:[1,0]
	v_pk_mul_f32 v[66:67], v[66:67], v[84:85] op_sel_hi:[1,0]
	v_pk_mul_f32 v[68:69], v[68:69], v[84:85] op_sel_hi:[1,0]
	v_pk_add_f32 v[86:87], v[86:87], s[100:101] op_sel_hi:[1,0]
	v_pk_add_f32 v[88:89], v[88:89], s[100:101] op_sel_hi:[1,0]
	v_pk_add_f32 v[90:91], v[90:91], s[100:101] op_sel_hi:[1,0]
	v_pk_add_f32 v[92:93], v[92:93], s[100:101] op_sel_hi:[1,0]
	v_rcp_f32_e32 v86, v86
	v_rcp_f32_e32 v87, v87
	v_rcp_f32_e32 v88, v88
	v_rcp_f32_e32 v89, v89
	v_rcp_f32_e32 v90, v90
	v_rcp_f32_e32 v91, v91
	v_rcp_f32_e32 v92, v92
	v_rcp_f32_e32 v93, v93
	v_pk_mul_f32 v[78:79], v[78:79], v[86:87]
	v_pk_mul_f32 v[80:81], v[80:81], v[88:89]
	v_pk_mul_f32 v[74:75], v[74:75], v[90:91]
	v_pk_mul_f32 v[76:77], v[76:77], v[92:93]
	v_pk_mul_f32 v[70:71], v[70:71], v[78:79]
	v_pk_mul_f32 v[72:73], v[72:73], v[80:81]
	v_pk_mul_f32 v[74:75], v[66:67], v[74:75]
	v_pk_mul_f32 v[76:77], v[68:69], v[76:77]
	v_cvt_pk_bf16_f32 v66, v70, v71
	v_cvt_pk_bf16_f32 v67, v72, v73
	v_cvt_pk_bf16_f32 v68, v74, v75
	v_cvt_pk_bf16_f32 v69, v76, v77
	v_mad_i64_i32 v[70:71], s[24:25], v82, s64, v[140:141]
	flat_store_dwordx4 v[70:71], v[66:69]
	s_mov_b64 s[24:25], -1
	s_nop 0
	v_add_u32_e32 v66, 0x80, v142
	s_cbranch_vccnz .LBB0_185
	s_cmp_eq_u32 s48, s12
	s_cbranch_scc1 .LBB0_182
	v_ashrrev_i32_e32 v67, 31, v66
	v_lshlrev_b64 v[68:69], 6, v[66:67]
	v_lshl_add_u64 v[80:81], s[38:39], 0, v[68:69]
	flat_load_dwordx4 v[68:71], v[80:81]
	flat_load_dwordx4 v[72:75], v[80:81] offset:16
	flat_load_dwordx4 v[76:79], v[80:81] offset:32
	s_nop 0
	flat_load_dwordx4 v[80:83], v[80:81] offset:48
	s_mov_b64 s[24:25], 0
	s_waitcnt vmcnt(0) lgkmcnt(0)
	v_mov_b32_e32 v84, v69
	v_mov_b32_e32 v85, v70
	v_mov_b32_e32 v69, v71
	v_mov_b32_e32 v70, v73
	v_mov_b32_e32 v71, v74
	v_mov_b32_e32 v73, v75
	v_pk_add_f32 v[68:69], v[84:85], v[68:69]
	v_pk_add_f32 v[70:71], v[70:71], v[72:73]
	v_pk_add_f32 v[68:69], v[68:69], v[68:69] op_sel:[0,1] op_sel_hi:[1,0]
	v_pk_add_f32 v[70:71], v[70:71], v[70:71] op_sel:[0,1] op_sel_hi:[1,0]
	v_add_f32_e32 v72, v76, v77
	v_add_f32_e32 v74, v78, v79
	v_mov_b32_e32 v69, v80
	v_mov_b32_e32 v71, v81
	v_mov_b32_e32 v73, v82
	v_mov_b32_e32 v75, v83
	v_pk_add_f32 v[68:69], v[68:69], v[70:71]
	v_pk_add_f32 v[70:71], v[72:73], v[74:75]
	s_nop 0
	v_pk_add_f32 v[68:69], v[68:69], v[70:71]
	s_nop 0
	v_add_f32_e32 v67, v68, v69
	v_fmamk_f32 v67, v67, 0x3a800000, v205
	v_cmp_gt_f32_e32 vcc, s77, v67
	v_mul_f32_e32 v68, 0x4b800000, v67
	s_nop 0
	v_cndmask_b32_e32 v67, v67, v68, vcc
	v_rsq_f32_e32 v67, v67
	s_nop 0
	v_mul_f32_e32 v68, 0x45800000, v67
	v_cndmask_b32_e32 v68, v67, v68, vcc

; __device__ __forceinline__ u32x4 pack8(f32x4 a, f32x4 b) { u32x4 w; w.x = pk2(a[0], a[1]); w.y = pk2(a[2], a[3]); w.z = pk2(b[0], b[1]); w.w = pk2(b[2], b[3]); return w; }
; __device__ __forceinline__ float fast_sigmoid(float x) { return __builtin_amdgcn_rcpf(1.0f + __builtin_amdgcn_exp2f(-x * LOG2E)); }
; __device__ __forceinline__ float row_rs16(const float* ssq_x, int row) {
;     const f32x4* p = (const f32x4*)(ssq_x + (size_t)row * 16); const f32x4 a = p[0], b = p[1], c = p[2], d = p[3];
;     return rsqrtf((((a[0] + a[1]) + (a[2] + a[3])) + ((b[0] + b[1]) + (b[2] + b[3])) + ((c[0] + c[1]) + (c[2] + c[3])) + ((d[0] + d[1]) + (d[2] + d[3]))) * (1.0f / DM) + EPS);
; }
;     __device__ __forceinline__ void operator()(const Acc& acc, const Unit& u, int wr, int wc, int fr, int fq, const RsCtx& rc) const {
;     ...
;             for (int m = 0; m < 4; ++m) { const int row = EPI_ROW(u, ai, wr, m, fr); const float rs = rc.get(u.pm, ai * 128 + wr * 64 + m * 16 + fr, row);
;                 f32x4 a0 = acc[ai][0][m][0] * rs, a1 = acc[ai][0][m][1] * rs; const f32x4 b0 = acc[ai][1][m][0] * rs, b1 = acc[ai][1][m][1] * rs;
; #pragma unroll
;                 for (int e = 0; e < 4; ++e) { a0[e] = a0[e] * fast_sigmoid(a0[e]) * b0[e]; a1[e] = a1[e] * fast_sigmoid(a1[e]) * b1[e]; }
;                 *(u32x4*)(O + (size_t)row * FF + col) = pack8(a0, a1);
.LBB0_187:
	s_waitcnt lgkmcnt(0)
	s_and_b64 vcc, exec, s[6:7]
	s_mov_b32 s100, 0xbfb8aa3b
	v_pk_mul_f32 v[62:63], v[62:63], v[68:69] op_sel_hi:[1,0]
	v_pk_mul_f32 v[64:65], v[64:65], v[68:69] op_sel_hi:[1,0]
	v_pk_mul_f32 v[58:59], v[58:59], v[68:69] op_sel_hi:[1,0]
	v_pk_mul_f32 v[60:61], v[60:61], v[68:69] op_sel_hi:[1,0]
	v_pk_mul_f32 v[70:71], v[62:63], s[100:101] op_sel_hi:[1,0]
	v_pk_mul_f32 v[72:73], v[64:65], s[100:101] op_sel_hi:[1,0]
	v_pk_mul_f32 v[74:75], v[58:59], s[100:101] op_sel_hi:[1,0]
	v_pk_mul_f32 v[76:77], v[60:61], s[100:101] op_sel_hi:[1,0]
	s_mov_b32 s100, 1.0
	v_exp_f32_e32 v70, v70
	v_exp_f32_e32 v71, v71
	v_exp_f32_e32 v72, v72
	v_exp_f32_e32 v73, v73
	v_exp_f32_e32 v74, v74
	v_exp_f32_e32 v75, v75
	v_exp_f32_e32 v76, v76
	v_exp_f32_e32 v77, v77
	v_pk_mul_f32 v[54:55], v[54:55], v[68:69] op_sel_hi:[1,0]
	v_pk_mul_f32 v[56:57], v[56:57], v[68:69] op_sel_hi:[1,0]
	v_pk_mul_f32 v[50:51], v[50:51], v[68:69] op_sel_hi:[1,0]
	v_pk_mul_f32 v[52:53], v[52:53], v[68:69] op_sel_hi:[1,0]
	v_pk_add_f32 v[70:71], v[70:71], s[100:101] op_sel_hi:[1,0]
	v_pk_add_f32 v[72:73], v[72:73], s[100:101] op_sel_hi:[1,0]
	v_pk_add_f32 v[74:75], v[74:75], s[100:101] op_sel_hi:[1,0]
	v_pk_add_f32 v[76:77], v[76:77], s[100:101] op_sel_hi:[1,0]
	v_rcp_f32_e32 v70, v70
	v_rcp_f32_e32 v71, v71
	v_rcp_f32_e32 v72, v72
	v_rcp_f32_e32 v73, v73
	v_rcp_f32_e32 v74, v74
	v_rcp_f32_e32 v75, v75
	v_rcp_f32_e32 v76, v76
	v_rcp_f32_e32 v77, v77
	v_pk_mul_f32 v[62:63], v[62:63], v[70:71]
	v_pk_mul_f32 v[64:65], v[64:65], v[72:73]
	v_pk_mul_f32 v[58:59], v[58:59], v[74:75]
	v_pk_mul_f32 v[60:61], v[60:61], v[76:77]
	v_pk_mul_f32 v[54:55], v[54:55], v[62:63]
	v_pk_mul_f32 v[56:57], v[56:57], v[64:65]
	v_pk_mul_f32 v[58:59], v[50:51], v[58:59]
	v_pk_mul_f32 v[60:61], v[52:53], v[60:61]
	v_cvt_pk_bf16_f32 v50, v54, v55
	v_cvt_pk_bf16_f32 v51, v56, v57
	v_cvt_pk_bf16_f32 v52, v58, v59
	v_cvt_pk_bf16_f32 v53, v60, v61
	v_mad_i64_i32 v[54:55], s[24:25], v66, s64, v[140:141]
	flat_store_dwordx4 v[54:55], v[50:53]
	s_mov_b64 s[24:25], -1
	s_nop 0
	v_add_u32_e32 v50, 0x90, v142
	s_cbranch_vccnz .LBB0_193
	s_cmp_eq_u32 s48, s12
	s_cbranch_scc1 .LBB0_190
	v_ashrrev_i32_e32 v51, 31, v50
	v_lshlrev_b64 v[52:53], 6, v[50:51]
	v_lshl_add_u64 v[64:65], s[38:39], 0, v[52:53]
	flat_load_dwordx4 v[52:55], v[64:65]
	flat_load_dwordx4 v[56:59], v[64:65] offset:16
	flat_load_dwordx4 v[60:63], v[64:65] offset:32
	s_nop 0
	flat_load_dwordx4 v[64:67], v[64:65] offset:48
	s_mov_b64 s[24:25], 0
	s_waitcnt vmcnt(0) lgkmcnt(0)
	v_mov_b32_e32 v68, v53
	v_mov_b32_e32 v69, v54
	v_mov_b32_e32 v53, v55
	v_mov_b32_e32 v54, v57
	v_mov_b32_e32 v55, v58
	v_mov_b32_e32 v57, v59
	v_pk_add_f32 v[52:53], v[68:69], v[52:53]
	v_pk_add_f32 v[54:55], v[54:55], v[56:57]
	v_pk_add_f32 v[52:53], v[52:53], v[52:53] op_sel:[0,1] op_sel_hi:[1,0]
	v_pk_add_f32 v[54:55], v[54:55], v[54:55] op_sel:[0,1] op_sel_hi:[1,0]
	v_add_f32_e32 v56, v60, v61
	v_add_f32_e32 v58, v62, v63
	v_mov_b32_e32 v53, v64
	v_mov_b32_e32 v55, v65
	v_mov_b32_e32 v57, v66
	v_mov_b32_e32 v59, v67
	v_pk_add_f32 v[52:53], v[52:53], v[54:55]
	v_pk_add_f32 v[54:55], v[56:57], v[58:59]
	s_nop 0
	v_pk_add_f32 v[52:53], v[52:53], v[54:55]
	s_nop 0
	v_add_f32_e32 v51, v52, v53
	v_fmamk_f32 v51, v51, 0x3a800000, v205
	v_cmp_gt_f32_e32 vcc, s77, v51
	v_mul_f32_e32 v52, 0x4b800000, v51
	s_nop 0
	v_cndmask_b32_e32 v51, v51, v52, vcc
	v_rsq_f32_e32 v51, v51
	s_nop 0
	v_mul_f32_e32 v52, 0x45800000, v51
	v_cndmask_b32_e32 v52, v51, v52, vcc

; __device__ __forceinline__ u32x4 pack8(f32x4 a, f32x4 b) { u32x4 w; w.x = pk2(a[0], a[1]); w.y = pk2(a[2], a[3]); w.z = pk2(b[0], b[1]); w.w = pk2(b[2], b[3]); return w; }
; __device__ __forceinline__ float fast_sigmoid(float x) { return __builtin_amdgcn_rcpf(1.0f + __builtin_amdgcn_exp2f(-x * LOG2E)); }
; __device__ __forceinline__ float row_rs16(const float* ssq_x, int row) {
;     const f32x4* p = (const f32x4*)(ssq_x + (size_t)row * 16); const f32x4 a = p[0], b = p[1], c = p[2], d = p[3];
;     return rsqrtf((((a[0] + a[1]) + (a[2] + a[3])) + ((b[0] + b[1]) + (b[2] + b[3])) + ((c[0] + c[1]) + (c[2] + c[3])) + ((d[0] + d[1]) + (d[2] + d[3]))) * (1.0f / DM) + EPS);
; }
;     __device__ __forceinline__ void operator()(const Acc& acc, const Unit& u, int wr, int wc, int fr, int fq, const RsCtx& rc) const {
;     ...
;             for (int m = 0; m < 4; ++m) { const int row = EPI_ROW(u, ai, wr, m, fr); const float rs = rc.get(u.pm, ai * 128 + wr * 64 + m * 16 + fr, row);
;                 f32x4 a0 = acc[ai][0][m][0] * rs, a1 = acc[ai][0][m][1] * rs; const f32x4 b0 = acc[ai][1][m][0] * rs, b1 = acc[ai][1][m][1] * rs;
; #pragma unroll
;                 for (int e = 0; e < 4; ++e) { a0[e] = a0[e] * fast_sigmoid(a0[e]) * b0[e]; a1[e] = a1[e] * fast_sigmoid(a1[e]) * b1[e]; }
;                 *(u32x4*)(O + (size_t)row * FF + col) = pack8(a0, a1);
.LBB0_195:
	s_waitcnt lgkmcnt(0)
	s_and_b64 vcc, exec, s[6:7]
	s_mov_b32 s100, 0xbfb8aa3b
	v_pk_mul_f32 v[46:47], v[46:47], v[52:53] op_sel_hi:[1,0]
	v_pk_mul_f32 v[48:49], v[48:49], v[52:53] op_sel_hi:[1,0]
	v_pk_mul_f32 v[42:43], v[42:43], v[52:53] op_sel_hi:[1,0]
	v_pk_mul_f32 v[44:45], v[44:45], v[52:53] op_sel_hi:[1,0]
	v_pk_mul_f32 v[54:55], v[46:47], s[100:101] op_sel_hi:[1,0]
	v_pk_mul_f32 v[56:57], v[48:49], s[100:101] op_sel_hi:[1,0]
	v_pk_mul_f32 v[58:59], v[42:43], s[100:101] op_sel_hi:[1,0]
	v_pk_mul_f32 v[60:61], v[44:45], s[100:101] op_sel_hi:[1,0]
	s_mov_b32 s100, 1.0
	v_exp_f32_e32 v54, v54
	v_exp_f32_e32 v55, v55
	v_exp_f32_e32 v56, v56
	v_exp_f32_e32 v57, v57
	v_exp_f32_e32 v58, v58
	v_exp_f32_e32 v59, v59
	v_exp_f32_e32 v60, v60
	v_exp_f32_e32 v61, v61
	v_pk_mul_f32 v[38:39], v[38:39], v[52:53] op_sel_hi:[1,0]
	v_pk_mul_f32 v[40:41], v[40:41], v[52:53] op_sel_hi:[1,0]
	v_pk_mul_f32 v[34:35], v[34:35], v[52:53] op_sel_hi:[1,0]
	v_pk_mul_f32 v[36:37], v[36:37], v[52:53] op_sel_hi:[1,0]
	v_pk_add_f32 v[54:55], v[54:55], s[100:101] op_sel_hi:[1,0]
	v_pk_add_f32 v[56:57], v[56:57], s[100:101] op_sel_hi:[1,0]
	v_pk_add_f32 v[58:59], v[58:59], s[100:101] op_sel_hi:[1,0]
	v_pk_add_f32 v[60:61], v[60:61], s[100:101] op_sel_hi:[1,0]
	v_rcp_f32_e32 v54, v54
	v_rcp_f32_e32 v55, v55
	v_rcp_f32_e32 v56, v56
	v_rcp_f32_e32 v57, v57
	v_rcp_f32_e32 v58, v58
	v_rcp_f32_e32 v59, v59
	v_rcp_f32_e32 v60, v60
	v_rcp_f32_e32 v61, v61
	v_pk_mul_f32 v[46:47], v[46:47], v[54:55]
	v_pk_mul_f32 v[48:49], v[48:49], v[56:57]
	v_pk_mul_f32 v[42:43], v[42:43], v[58:59]
	v_pk_mul_f32 v[44:45], v[44:45], v[60:61]
	v_pk_mul_f32 v[38:39], v[38:39], v[46:47]
	v_pk_mul_f32 v[40:41], v[40:41], v[48:49]
	v_pk_mul_f32 v[42:43], v[34:35], v[42:43]
	v_pk_mul_f32 v[44:45], v[36:37], v[44:45]
	v_cvt_pk_bf16_f32 v34, v38, v39
	v_cvt_pk_bf16_f32 v35, v40, v41
	v_cvt_pk_bf16_f32 v36, v42, v43
	v_cvt_pk_bf16_f32 v37, v44, v45
	v_mad_i64_i32 v[38:39], s[24:25], v50, s64, v[140:141]
	flat_store_dwordx4 v[38:39], v[34:37]
	s_mov_b64 s[24:25], -1
	s_nop 0
	v_add_u32_e32 v34, 0xa0, v142
	s_cbranch_vccnz .LBB0_201
	s_cmp_eq_u32 s48, s12
	s_cbranch_scc1 .LBB0_198
	v_ashrrev_i32_e32 v35, 31, v34
	v_lshlrev_b64 v[36:37], 6, v[34:35]
	v_lshl_add_u64 v[48:49], s[38:39], 0, v[36:37]
	flat_load_dwordx4 v[36:39], v[48:49]
	flat_load_dwordx4 v[40:43], v[48:49] offset:16
	flat_load_dwordx4 v[44:47], v[48:49] offset:32
	s_nop 0
	flat_load_dwordx4 v[48:51], v[48:49] offset:48
	s_mov_b64 s[24:25], 0
	s_waitcnt vmcnt(0) lgkmcnt(0)
	v_mov_b32_e32 v52, v37
	v_mov_b32_e32 v53, v38
	v_mov_b32_e32 v37, v39
	v_mov_b32_e32 v38, v41
	v_mov_b32_e32 v39, v42
	v_mov_b32_e32 v41, v43
	v_pk_add_f32 v[36:37], v[52:53], v[36:37]
	v_pk_add_f32 v[38:39], v[38:39], v[40:41]
	v_pk_add_f32 v[36:37], v[36:37], v[36:37] op_sel:[0,1] op_sel_hi:[1,0]
	v_pk_add_f32 v[38:39], v[38:39], v[38:39] op_sel:[0,1] op_sel_hi:[1,0]
	v_add_f32_e32 v40, v44, v45
	v_add_f32_e32 v42, v46, v47
	v_mov_b32_e32 v37, v48
	v_mov_b32_e32 v39, v49
	v_mov_b32_e32 v41, v50
	v_mov_b32_e32 v43, v51
	v_pk_add_f32 v[36:37], v[36:37], v[38:39]
	v_pk_add_f32 v[38:39], v[40:41], v[42:43]
	s_nop 0
	v_pk_add_f32 v[36:37], v[36:37], v[38:39]
	s_nop 0
	v_add_f32_e32 v35, v36, v37
	v_fmamk_f32 v35, v35, 0x3a800000, v205
	v_cmp_gt_f32_e32 vcc, s77, v35
	v_mul_f32_e32 v36, 0x4b800000, v35
	s_nop 0
	v_cndmask_b32_e32 v35, v35, v36, vcc
	v_rsq_f32_e32 v35, v35
	s_nop 0
	v_mul_f32_e32 v36, 0x45800000, v35
	v_cndmask_b32_e32 v36, v35, v36, vcc

; __device__ __forceinline__ u32x4 pack8(f32x4 a, f32x4 b) { u32x4 w; w.x = pk2(a[0], a[1]); w.y = pk2(a[2], a[3]); w.z = pk2(b[0], b[1]); w.w = pk2(b[2], b[3]); return w; }
; __device__ __forceinline__ float fast_sigmoid(float x) { return __builtin_amdgcn_rcpf(1.0f + __builtin_amdgcn_exp2f(-x * LOG2E)); }
; __device__ __forceinline__ float row_rs16(const float* ssq_x, int row) {
;     const f32x4* p = (const f32x4*)(ssq_x + (size_t)row * 16); const f32x4 a = p[0], b = p[1], c = p[2], d = p[3];
;     return rsqrtf((((a[0] + a[1]) + (a[2] + a[3])) + ((b[0] + b[1]) + (b[2] + b[3])) + ((c[0] + c[1]) + (c[2] + c[3])) + ((d[0] + d[1]) + (d[2] + d[3]))) * (1.0f / DM) + EPS);
; }
;     __device__ __forceinline__ void operator()(const Acc& acc, const Unit& u, int wr, int wc, int fr, int fq, const RsCtx& rc) const {
;     ...
;             for (int m = 0; m < 4; ++m) { const int row = EPI_ROW(u, ai, wr, m, fr); const float rs = rc.get(u.pm, ai * 128 + wr * 64 + m * 16 + fr, row);
;                 f32x4 a0 = acc[ai][0][m][0] * rs, a1 = acc[ai][0][m][1] * rs; const f32x4 b0 = acc[ai][1][m][0] * rs, b1 = acc[ai][1][m][1] * rs;
; #pragma unroll
;                 for (int e = 0; e < 4; ++e) { a0[e] = a0[e] * fast_sigmoid(a0[e]) * b0[e]; a1[e] = a1[e] * fast_sigmoid(a1[e]) * b1[e]; }
;                 *(u32x4*)(O + (size_t)row * FF + col) = pack8(a0, a1);
.LBB0_203:
	s_waitcnt lgkmcnt(0)
	s_and_b64 vcc, exec, s[6:7]
	s_mov_b32 s100, 0xbfb8aa3b
	v_pk_mul_f32 v[30:31], v[30:31], v[36:37] op_sel_hi:[1,0]
	v_pk_mul_f32 v[32:33], v[32:33], v[36:37] op_sel_hi:[1,0]
	v_pk_mul_f32 v[26:27], v[26:27], v[36:37] op_sel_hi:[1,0]
	v_pk_mul_f32 v[28:29], v[28:29], v[36:37] op_sel_hi:[1,0]
	v_pk_mul_f32 v[38:39], v[30:31], s[100:101] op_sel_hi:[1,0]
	v_pk_mul_f32 v[40:41], v[32:33], s[100:101] op_sel_hi:[1,0]
	v_pk_mul_f32 v[42:43], v[26:27], s[100:101] op_sel_hi:[1,0]
	v_pk_mul_f32 v[44:45], v[28:29], s[100:101] op_sel_hi:[1,0]
	s_mov_b32 s100, 1.0
	v_exp_f32_e32 v38, v38
	v_exp_f32_e32 v39, v39
	v_exp_f32_e32 v40, v40
	v_exp_f32_e32 v41, v41
	v_exp_f32_e32 v42, v42
	v_exp_f32_e32 v43, v43
	v_exp_f32_e32 v44, v44
	v_exp_f32_e32 v45, v45
	v_pk_mul_f32 v[22:23], v[22:23], v[36:37] op_sel_hi:[1,0]
	v_pk_mul_f32 v[24:25], v[24:25], v[36:37] op_sel_hi:[1,0]
	v_pk_mul_f32 v[18:19], v[18:19], v[36:37] op_sel_hi:[1,0]
	v_pk_mul_f32 v[20:21], v[20:21], v[36:37] op_sel_hi:[1,0]
	v_pk_add_f32 v[38:39], v[38:39], s[100:101] op_sel_hi:[1,0]
	v_pk_add_f32 v[40:41], v[40:41], s[100:101] op_sel_hi:[1,0]
	v_pk_add_f32 v[42:43], v[42:43], s[100:101] op_sel_hi:[1,0]
	v_pk_add_f32 v[44:45], v[44:45], s[100:101] op_sel_hi:[1,0]
	v_rcp_f32_e32 v38, v38
	v_rcp_f32_e32 v39, v39
	v_rcp_f32_e32 v40, v40
	v_rcp_f32_e32 v41, v41
	v_rcp_f32_e32 v42, v42
	v_rcp_f32_e32 v43, v43
	v_rcp_f32_e32 v44, v44
	v_rcp_f32_e32 v45, v45
	v_pk_mul_f32 v[30:31], v[30:31], v[38:39]
	v_pk_mul_f32 v[32:33], v[32:33], v[40:41]
	v_pk_mul_f32 v[26:27], v[26:27], v[42:43]
	v_pk_mul_f32 v[28:29], v[28:29], v[44:45]
	v_pk_mul_f32 v[22:23], v[22:23], v[30:31]
	v_pk_mul_f32 v[24:25], v[24:25], v[32:33]
	v_pk_mul_f32 v[26:27], v[18:19], v[26:27]
	v_pk_mul_f32 v[28:29], v[20:21], v[28:29]
	v_cvt_pk_bf16_f32 v18, v22, v23
	v_cvt_pk_bf16_f32 v19, v24, v25
	v_cvt_pk_bf16_f32 v20, v26, v27
	v_cvt_pk_bf16_f32 v21, v28, v29
	v_mad_i64_i32 v[22:23], s[24:25], v34, s64, v[140:141]
	flat_store_dwordx4 v[22:23], v[18:21]
	s_mov_b64 s[24:25], -1
	s_nop 0
	v_add_u32_e32 v18, 0xb0, v142
	s_cbranch_vccnz .LBB0_209
	s_cmp_eq_u32 s48, s12
	s_mov_b64 s[6:7], -1
	s_cbranch_scc1 .LBB0_206
	v_ashrrev_i32_e32 v19, 31, v18
	v_lshlrev_b64 v[20:21], 6, v[18:19]
	v_lshl_add_u64 v[32:33], s[38:39], 0, v[20:21]
	flat_load_dwordx4 v[20:23], v[32:33]
	flat_load_dwordx4 v[24:27], v[32:33] offset:16
	flat_load_dwordx4 v[28:31], v[32:33] offset:32
	s_nop 0
	flat_load_dwordx4 v[32:35], v[32:33] offset:48
	s_mov_b64 s[6:7], 0
	s_waitcnt vmcnt(0) lgkmcnt(0)
	v_mov_b32_e32 v36, v21
	v_mov_b32_e32 v37, v22
	v_mov_b32_e32 v21, v23
	v_mov_b32_e32 v22, v25
	v_mov_b32_e32 v23, v26
	v_mov_b32_e32 v25, v27
	v_pk_add_f32 v[20:21], v[36:37], v[20:21]
	v_pk_add_f32 v[22:23], v[22:23], v[24:25]
	v_pk_add_f32 v[20:21], v[20:21], v[20:21] op_sel:[0,1] op_sel_hi:[1,0]
	v_pk_add_f32 v[22:23], v[22:23], v[22:23] op_sel:[0,1] op_sel_hi:[1,0]
	v_add_f32_e32 v24, v28, v29
	v_add_f32_e32 v26, v30, v31
	v_mov_b32_e32 v21, v32
	v_mov_b32_e32 v23, v33
	v_mov_b32_e32 v25, v34
	v_mov_b32_e32 v27, v35
	v_pk_add_f32 v[20:21], v[20:21], v[22:23]
	v_pk_add_f32 v[22:23], v[24:25], v[26:27]
	s_nop 0
	v_pk_add_f32 v[20:21], v[20:21], v[22:23]
	s_nop 0
	v_add_f32_e32 v19, v20, v21
	v_fmamk_f32 v19, v19, 0x3a800000, v205
	v_cmp_gt_f32_e32 vcc, s77, v19
	v_mul_f32_e32 v20, 0x4b800000, v19
	s_nop 0
	v_cndmask_b32_e32 v19, v19, v20, vcc
	v_rsq_f32_e32 v19, v19
	s_nop 0
	v_mul_f32_e32 v20, 0x45800000, v19
	v_cndmask_b32_e32 v20, v19, v20, vcc

; __device__ __forceinline__ u32x4 pack8(f32x4 a, f32x4 b) { u32x4 w; w.x = pk2(a[0], a[1]); w.y = pk2(a[2], a[3]); w.z = pk2(b[0], b[1]); w.w = pk2(b[2], b[3]); return w; }
; __device__ __forceinline__ float fast_sigmoid(float x) { return __builtin_amdgcn_rcpf(1.0f + __builtin_amdgcn_exp2f(-x * LOG2E)); }
; #define PG8_BAR __builtin_amdgcn_s_barrier()
; #define PG8_BAR __builtin_amdgcn_s_barrier()
; template <class Epi, class Sched>
; __device__ __forceinline__ void gemm_phase(LAS unsigned char* lds, const Gemm g, const Sched S, const Epi E, const int tid) {
;     ...
;         if (!has_next) break;
; #pragma unroll
;         for (int a = 0; a < 2; ++a)
; #pragma unroll
;             for (int b = 0; b < 2; ++b)
; #pragma unroll
;                 for (int m = 0; m < 4; ++m)
; #pragma unroll
;                     for (int n = 0; n < 2; ++n) acc[a][b][m][n] = (f32x4){0.f, 0.f, 0.f, 0.f};
;         cur = nxt; cA = nA; cB = nB; ++ui;
;         if (wr == 1) PG8_BAR;
;     __device__ __forceinline__ void operator()(const Acc& acc, const Unit& u, int wr, int wc, int fr, int fq, const RsCtx& rc) const {
;     ...
;             for (int m = 0; m < 4; ++m) { const int row = EPI_ROW(u, ai, wr, m, fr); const float rs = rc.get(u.pm, ai * 128 + wr * 64 + m * 16 + fr, row);
;                 f32x4 a0 = acc[ai][0][m][0] * rs, a1 = acc[ai][0][m][1] * rs; const f32x4 b0 = acc[ai][1][m][0] * rs, b1 = acc[ai][1][m][1] * rs;
; #pragma unroll
;                 for (int e = 0; e < 4; ++e) { a0[e] = a0[e] * fast_sigmoid(a0[e]) * b0[e]; a1[e] = a1[e] * fast_sigmoid(a1[e]) * b1[e]; }
;                 *(u32x4*)(O + (size_t)row * FF + col) = pack8(a0, a1);
;                 if (m == 3) asm volatile("" ::: "memory"); }
.LBB0_211:
	s_waitcnt lgkmcnt(0)
	s_andn2_b64 vcc, exec, s[4:5]
	s_mov_b32 s100, 0xbfb8aa3b
	v_pk_mul_f32 v[14:15], v[14:15], v[20:21] op_sel_hi:[1,0]
	v_pk_mul_f32 v[16:17], v[16:17], v[20:21] op_sel_hi:[1,0]
	v_pk_mul_f32 v[10:11], v[10:11], v[20:21] op_sel_hi:[1,0]
	v_pk_mul_f32 v[12:13], v[12:13], v[20:21] op_sel_hi:[1,0]
	v_pk_mul_f32 v[22:23], v[14:15], s[100:101] op_sel_hi:[1,0]
	v_pk_mul_f32 v[24:25], v[16:17], s[100:101] op_sel_hi:[1,0]
	v_pk_mul_f32 v[26:27], v[10:11], s[100:101] op_sel_hi:[1,0]
	v_pk_mul_f32 v[28:29], v[12:13], s[100:101] op_sel_hi:[1,0]
	s_mov_b32 s100, 1.0
	v_exp_f32_e32 v22, v22
	v_exp_f32_e32 v23, v23
	v_exp_f32_e32 v24, v24
	v_exp_f32_e32 v25, v25
	v_exp_f32_e32 v26, v26
	v_exp_f32_e32 v27, v27
	v_exp_f32_e32 v28, v28
	v_exp_f32_e32 v29, v29
	v_pk_mul_f32 v[6:7], v[6:7], v[20:21] op_sel_hi:[1,0]
	v_pk_mul_f32 v[8:9], v[8:9], v[20:21] op_sel_hi:[1,0]
	v_pk_mul_f32 v[2:3], v[2:3], v[20:21] op_sel_hi:[1,0]
	v_pk_mul_f32 v[4:5], v[4:5], v[20:21] op_sel_hi:[1,0]
	v_pk_add_f32 v[22:23], v[22:23], s[100:101] op_sel_hi:[1,0]
	v_pk_add_f32 v[24:25], v[24:25], s[100:101] op_sel_hi:[1,0]
	v_pk_add_f32 v[26:27], v[26:27], s[100:101] op_sel_hi:[1,0]
	v_pk_add_f32 v[28:29], v[28:29], s[100:101] op_sel_hi:[1,0]
	v_rcp_f32_e32 v22, v22
	v_rcp_f32_e32 v23, v23
	v_rcp_f32_e32 v24, v24
	v_rcp_f32_e32 v25, v25
	v_rcp_f32_e32 v26, v26
	v_rcp_f32_e32 v27, v27
	v_rcp_f32_e32 v28, v28
	v_rcp_f32_e32 v29, v29
	v_pk_mul_f32 v[14:15], v[14:15], v[22:23]
	v_pk_mul_f32 v[16:17], v[16:17], v[24:25]
	v_pk_mul_f32 v[10:11], v[10:11], v[26:27]
	v_pk_mul_f32 v[12:13], v[12:13], v[28:29]
	v_pk_mul_f32 v[6:7], v[6:7], v[14:15]
	v_pk_mul_f32 v[8:9], v[8:9], v[16:17]
	v_pk_mul_f32 v[10:11], v[2:3], v[10:11]
	v_pk_mul_f32 v[12:13], v[4:5], v[12:13]
	v_cvt_pk_bf16_f32 v2, v6, v7
	v_cvt_pk_bf16_f32 v3, v8, v9
	v_cvt_pk_bf16_f32 v4, v10, v11
	v_cvt_pk_bf16_f32 v5, v12, v13
	v_mad_i64_i32 v[6:7], s[6:7], v18, s64, v[140:141]
	flat_store_dwordx4 v[6:7], v[2:5]
	s_mov_b64 s[6:7], -1
	s_cbranch_vccnz .LBB0_138
	s_andn2_b64 vcc, exec, s[8:9]
	s_cbranch_vccnz .LBB0_137
	s_barrier
	s_branch .LBB0_137

; __global__ void __launch_bounds__(512, 2) mk_fwd(Args a) {
	.amdhsa_kernel _Z6mk_fwd4Args
		.amdhsa_group_segment_fixed_size 0
		.amdhsa_private_segment_fixed_size 0
		.amdhsa_kernarg_size 448
		.amdhsa_user_sgpr_count 2
		.amdhsa_user_sgpr_dispatch_ptr 0
		.amdhsa_user_sgpr_queue_ptr 0
		.amdhsa_user_sgpr_kernarg_segment_ptr 1
		.amdhsa_user_sgpr_dispatch_id 0
		.amdhsa_user_sgpr_kernarg_preload_length 0
		.amdhsa_user_sgpr_kernarg_preload_offset 0
		.amdhsa_user_sgpr_private_segment_size 0
		.amdhsa_uses_dynamic_stack 0
		.amdhsa_enable_private_segment 0
		.amdhsa_system_sgpr_workgroup_id_x 1
		.amdhsa_system_sgpr_workgroup_id_y 0
		.amdhsa_system_sgpr_workgroup_id_z 0
		.amdhsa_system_sgpr_workgroup_info 0
		.amdhsa_system_vgpr_workitem_id 2
		.amdhsa_next_free_vgpr 256
		.amdhsa_next_free_sgpr 102
		.amdhsa_accum_offset 256
		.amdhsa_reserve_vcc 1
		.amdhsa_float_round_mode_32 0
		.amdhsa_float_round_mode_16_64 0
		.amdhsa_float_denorm_mode_32 3
		.amdhsa_float_denorm_mode_16_64 3
		.amdhsa_dx10_clamp 1
		.amdhsa_ieee_mode 1
		.amdhsa_fp16_overflow 0
		.amdhsa_tg_split 0
		.amdhsa_exception_fp_ieee_invalid_op 0
		.amdhsa_exception_fp_denorm_src 0
		.amdhsa_exception_fp_ieee_div_zero 0
		.amdhsa_exception_fp_ieee_overflow 0
		.amdhsa_exception_fp_ieee_underflow 0
		.amdhsa_exception_fp_ieee_inexact 0
		.amdhsa_exception_int_div_zero 0
	.end_amdhsa_kernel

; __global__ void __launch_bounds__(512, 2) mk_fwd(Args a) {
amdhsa.kernels:
  - .agpr_count:     0
    .args:
      - .offset:         0
        .size:           192
        .value_kind:     by_value
      - .offset:         192
        .size:           4
        .value_kind:     hidden_block_count_x
      - .offset:         196
        .size:           4
        .value_kind:     hidden_block_count_y
      - .offset:         200
        .size:           4
        .value_kind:     hidden_block_count_z
      - .offset:         204
        .size:           2
        .value_kind:     hidden_group_size_x
      - .offset:         206
        .size:           2
        .value_kind:     hidden_group_size_y
      - .offset:         208
        .size:           2
        .value_kind:     hidden_group_size_z
      - .offset:         210
        .size:           2
        .value_kind:     hidden_remainder_x
      - .offset:         212
        .size:           2
        .value_kind:     hidden_remainder_y
      - .offset:         214
        .size:           2
        .value_kind:     hidden_remainder_z
      - .offset:         232
        .size:           8
        .value_kind:     hidden_global_offset_x
      - .offset:         240
        .size:           8
        .value_kind:     hidden_global_offset_y
      - .offset:         248
        .size:           8
        .value_kind:     hidden_global_offset_z
      - .offset:         256
        .size:           2
        .value_kind:     hidden_grid_dims
      - .offset:         280
        .size:           8
        .value_kind:     hidden_multigrid_sync_arg
      - .offset:         312
        .size:           4
        .value_kind:     hidden_dynamic_lds_size
    .group_segment_fixed_size: 0
    .kernarg_segment_align: 8
    .kernarg_segment_size: 448
    .language:       OpenCL C
    .language_version:
      - 2
      - 0
    .max_flat_workgroup_size: 512
    .name:           _Z6mk_fwd4Args
    .private_segment_fixed_size: 0
    .sgpr_count:     108
    .sgpr_spill_count: 312
    .symbol:         _Z6mk_fwd4Args.kd
    .uniform_work_group_size: 1
    .uses_dynamic_stack: false
    .vgpr_count:     256
    .vgpr_spill_count: 0
    .wavefront_size: 64
